# v32 + MLA QK MFMA groups in alternating S0S0S1S1 / S1S1S0S0 order (chains of four, no distance-2/3 dependent MFMAs)
# baseline (speedup 1.0000x reference)
.LBB0_2904:
	v_add_u32_e32 v0, s28, v183
	ds_read_b128 v[2:5], v0 offset:24576
	ds_read_b128 v[6:9], v0 offset:28672
	ds_read_b128 v[10:13], v0 offset:32768
	ds_read_b128 v[184:187], v0 offset:36864
	v_exp_f32_e32 v14, v96
	v_exp_f32_e32 v190, v97
	v_exp_f32_e32 v98, v98
	v_exp_f32_e32 v192, v99
	v_exp_f32_e32 v15, v100
	v_exp_f32_e32 v191, v101
	v_exp_f32_e32 v99, v102
	v_exp_f32_e32 v193, v103
	v_add_u32_e32 v0, s28, v182
	v_pk_add_f32 v[96:97], v[14:15], v[190:191]
	v_pk_add_f32 v[100:101], v[98:99], v[192:193]
	s_nop 0
	v_pk_add_f32 v[96:97], v[96:97], v[100:101]
	v_cvt_pk_bf16_f32 v99, v99, v193
	v_pk_add_f32 v[202:203], v[96:97], v[96:97] op_sel_hi:[0,1]
	v_cvt_pk_bf16_f32 v96, v14, v190
	v_cvt_pk_bf16_f32 v97, v98, v192
	v_cvt_pk_bf16_f32 v98, v15, v191
	ds_read_b128 v[100:103], v0 offset:24576
	ds_read_b128 v[190:193], v0 offset:28672
	ds_read_b128 v[194:197], v0 offset:32768
	ds_read_b128 v[198:201], v0 offset:36864
	s_waitcnt lgkmcnt(0)
	v_mfma_f32_32x32x16_bf16 v[64:79], v[2:5], v[96:99], v[64:79]
	v_mfma_f32_32x32x16_bf16 v[48:63], v[6:9], v[96:99], v[48:63]
	v_mfma_f32_32x32x16_bf16 v[32:47], v[10:13], v[96:99], v[32:47]
	v_mfma_f32_32x32x16_bf16 v[16:31], v[184:187], v[96:99], v[16:31]
	v_exp_f32_e32 v2, v104
	v_exp_f32_e32 v4, v105
	v_exp_f32_e32 v3, v106
	v_exp_f32_e32 v5, v107
	v_exp_f32_e32 v6, v108
	v_exp_f32_e32 v8, v109
	v_exp_f32_e32 v7, v110
	v_exp_f32_e32 v9, v111
	v_pk_add_f32 v[10:11], v[2:3], v[4:5]
	v_add_u32_e32 v0, s28, v180
	v_pk_add_f32 v[14:15], v[10:11], v[10:11] op_sel_hi:[0,1]
	v_pk_add_f32 v[10:11], v[6:7], v[8:9]
	v_cvt_pk_bf16_f32 v2, v2, v4
	v_pk_add_f32 v[184:185], v[10:11], v[10:11] op_sel_hi:[0,1]
	v_cvt_pk_bf16_f32 v3, v3, v5
	v_cvt_pk_bf16_f32 v4, v6, v8
	v_cvt_pk_bf16_f32 v5, v7, v9
	ds_read_b128 v[6:9], v0 offset:24576
	ds_read_b128 v[10:13], v0 offset:28672
	ds_read_b128 v[96:99], v0 offset:32768
	ds_read_b128 v[104:107], v0 offset:36864
	v_mfma_f32_32x32x16_bf16 v[64:79], v[100:103], v[2:5], v[64:79]
	v_mfma_f32_32x32x16_bf16 v[48:63], v[190:193], v[2:5], v[48:63]
	v_mfma_f32_32x32x16_bf16 v[32:47], v[194:197], v[2:5], v[32:47]
	v_mfma_f32_32x32x16_bf16 v[16:31], v[198:201], v[2:5], v[16:31]
	v_exp_f32_e32 v0, v80
	v_exp_f32_e32 v2, v81
	v_exp_f32_e32 v3, v82
	v_exp_f32_e32 v4, v83
	v_exp_f32_e32 v5, v84
	v_exp_f32_e32 v14, v85
	v_exp_f32_e32 v80, v86
	v_exp_f32_e32 v81, v87
	v_add_f32_e32 v187, v0, v2
	v_cvt_pk_bf16_f32 v2, v0, v2
	v_add_u32_e32 v0, s28, v175
	v_add_f32_e32 v191, v3, v4
	v_add_f32_e32 v193, v5, v14
	v_add_f32_e32 v195, v80, v81
	v_cvt_pk_bf16_f32 v3, v3, v4
	v_cvt_pk_bf16_f32 v4, v5, v14
	v_cvt_pk_bf16_f32 v5, v80, v81
	ds_read_b128 v[80:83], v0 offset:24576
	ds_read_b128 v[84:87], v0 offset:28672
	ds_read_b128 v[100:103], v0 offset:32768
	ds_read_b128 v[108:111], v0 offset:36864
	s_waitcnt lgkmcnt(0)
	v_mfma_f32_32x32x16_bf16 v[64:79], v[6:9], v[2:5], v[64:79]
	v_mfma_f32_32x32x16_bf16 v[48:63], v[10:13], v[2:5], v[48:63]
	v_mfma_f32_32x32x16_bf16 v[32:47], v[96:99], v[2:5], v[32:47]
	v_mfma_f32_32x32x16_bf16 v[16:31], v[104:107], v[2:5], v[16:31]
	v_exp_f32_e32 v186, v88
	v_exp_f32_e32 v190, v89
	v_exp_f32_e32 v192, v90
	v_exp_f32_e32 v194, v91
	v_exp_f32_e32 v14, v92
	v_exp_f32_e32 v184, v93
	v_exp_f32_e32 v202, v94
	v_exp_f32_e32 v0, v95
	v_cvt_pk_bf16_f32 v2, v186, v190
	v_cvt_pk_bf16_f32 v3, v192, v194
	v_cvt_pk_bf16_f32 v4, v14, v184
	v_cvt_pk_bf16_f32 v5, v202, v0
	s_nop 1
	v_mfma_f32_32x32x16_bf16 v[64:79], v[80:83], v[2:5], v[64:79]
	v_add_f32_e64 v6, v186, v190
	v_add_f32_e64 v7, v187, v191
	v_add_f32_e64 v8, v192, v194
	v_add_f32_e64 v9, v193, v195
	v_add_f32_e64 v10, v202, v0
	v_add_f32_e64 v11, v203, v1
	v_pk_add_f32 v[6:7], v[6:7], v[8:9]
	v_pk_add_f32 v[8:9], v[14:15], v[184:185]
	s_nop 0
	v_pk_add_f32 v[8:9], v[8:9], v[10:11]
	v_mfma_f32_32x32x16_bf16 v[48:63], v[84:87], v[2:5], v[48:63]
	v_add_f32_e64 v6, v6, v8
	v_add_f32_e64 v7, v7, v9
	v_pk_add_f32 v[6:7], v[6:7], v[6:7] op_sel:[0,1] op_sel_hi:[1,0]
	v_mfma_f32_32x32x16_bf16 v[32:47], v[100:103], v[2:5], v[32:47]
	v_mfma_f32_32x32x16_bf16 v[16:31], v[108:111], v[2:5], v[16:31]
	v_mov_b32_e32 v0, v6
	s_nop 1
	v_permlane32_swap_b32_e32 v6, v0
	v_add_f32_e32 v0, v6, v0
	v_add_f32_e32 v171, v171, v0
	v_add_u32_e32 v0, s1, v174
	v_add_u32_e32 v14, s1, v173
	v_add_u32_e32 v15, s1, v170
	ds_read_b128 v[2:5], v0
	ds_read_b128 v[6:9], v0 offset:12288
	ds_read_b128 v[10:13], v14
	ds_read_b128 v[184:187], v14 offset:12288
	v_add_u32_e32 v206, s1, v172
	ds_read_b128 v[190:193], v15
	ds_read_b128 v[194:197], v15 offset:12288
	ds_read_b128 v[198:201], v206
	ds_read_b128 v[202:205], v206 offset:12288
	v_xor_b32_e32 v80, 0x80000000, v181
	v_mov_b32_e32 v81, v80
	v_mov_b32_e32 v82, v80
	v_mov_b32_e32 v83, v80
	v_mov_b32_e32 v84, v80
	v_mov_b32_e32 v85, v80
	v_mov_b32_e32 v86, v80
	v_mov_b32_e32 v87, v80
	v_mov_b32_e32 v88, v80
	v_mov_b32_e32 v89, v80
	v_mov_b32_e32 v90, v80
	v_mov_b32_e32 v91, v80
	v_mov_b32_e32 v92, v80
	v_mov_b32_e32 v93, v80
	v_mov_b32_e32 v94, v80
	v_mov_b32_e32 v95, v80
	s_waitcnt lgkmcnt(0)
	s_nop 0
	v_mfma_f32_32x32x16_bf16 v[96:111], v[2:5], v[112:115], v[80:95]
	v_mfma_f32_32x32x16_bf16 v[80:95], v[6:9], v[112:115], v[80:95]
	v_mfma_f32_32x32x16_bf16 v[80:95], v[184:187], v[116:119], v[80:95]
	v_mfma_f32_32x32x16_bf16 v[96:111], v[10:13], v[116:119], v[96:111]
	ds_read_b128 v[2:5], v14 offset:12416
	ds_read_b128 v[6:9], v14 offset:128
	ds_read_b128 v[10:13], v0 offset:12416
	ds_read_b128 v[184:187], v0 offset:128
	v_mfma_f32_32x32x16_bf16 v[96:111], v[190:193], v[120:123], v[96:111]
	v_mfma_f32_32x32x16_bf16 v[96:111], v[198:201], v[124:127], v[96:111]
	v_mfma_f32_32x32x16_bf16 v[80:95], v[194:197], v[120:123], v[80:95]
	v_mfma_f32_32x32x16_bf16 v[80:95], v[202:205], v[124:127], v[80:95]
	ds_read_b128 v[190:193], v15 offset:128
	ds_read_b128 v[194:197], v15 offset:12416
	ds_read_b128 v[198:201], v206 offset:128
	ds_read_b128 v[202:205], v206 offset:12416
	s_waitcnt lgkmcnt(0)
	v_mfma_f32_32x32x16_bf16 v[80:95], v[10:13], v[128:131], v[80:95]
	v_mfma_f32_32x32x16_bf16 v[80:95], v[2:5], v[132:135], v[80:95]
	v_mfma_f32_32x32x16_bf16 v[96:111], v[184:187], v[128:131], v[96:111]
	v_mfma_f32_32x32x16_bf16 v[96:111], v[6:9], v[132:135], v[96:111]
	ds_read_b128 v[2:5], v14 offset:12544
	ds_read_b128 v[6:9], v14 offset:256
	ds_read_b128 v[10:13], v0 offset:12544
	ds_read_b128 v[184:187], v0 offset:256
	v_mfma_f32_32x32x16_bf16 v[96:111], v[190:193], v[136:139], v[96:111]
	v_mfma_f32_32x32x16_bf16 v[96:111], v[198:201], v[140:143], v[96:111]
	v_mfma_f32_32x32x16_bf16 v[80:95], v[194:197], v[136:139], v[80:95]
	v_mfma_f32_32x32x16_bf16 v[80:95], v[202:205], v[140:143], v[80:95]
	ds_read_b128 v[190:193], v15 offset:256
	ds_read_b128 v[194:197], v15 offset:12544
	ds_read_b128 v[198:201], v206 offset:256
	ds_read_b128 v[202:205], v206 offset:12544
	s_waitcnt lgkmcnt(0)
	v_mfma_f32_32x32x16_bf16 v[80:95], v[10:13], v[144:147], v[80:95]
	v_mfma_f32_32x32x16_bf16 v[80:95], v[2:5], v[148:151], v[80:95]
	v_mfma_f32_32x32x16_bf16 v[96:111], v[184:187], v[144:147], v[96:111]
	v_mfma_f32_32x32x16_bf16 v[96:111], v[6:9], v[148:151], v[96:111]
	v_mfma_f32_32x32x16_bf16 v[96:111], v[190:193], v[152:155], v[96:111]
	v_mfma_f32_32x32x16_bf16 v[96:111], v[198:201], v[156:159], v[96:111]
	v_mfma_f32_32x32x16_bf16 v[80:95], v[194:197], v[152:155], v[80:95]
	s_nop 10
	v_max_f32_e32 v0, v97, v97
	v_max_f32_e32 v2, v96, v96
	v_max_f32_e32 v0, v2, v0
	v_max3_f32 v0, v0, v98, v99
	v_max3_f32 v0, v0, v100, v101
	v_max3_f32 v0, v0, v102, v103
	v_max3_f32 v0, v0, v104, v105
	v_mfma_f32_32x32x16_bf16 v[80:95], v[202:205], v[156:159], v[80:95]
	v_max3_f32 v0, v0, v106, v107
	v_max3_f32 v0, v0, v108, v109
	v_max3_f32 v0, v0, v110, v111
	s_mov_b32 s28, 0x41000000
	s_nop 7
	v_max3_f32 v0, v0, v80, v81
	v_max3_f32 v0, v0, v82, v83
	v_max3_f32 v0, v0, v84, v85
	v_max3_f32 v0, v0, v86, v87
	v_max3_f32 v0, v0, v88, v89
	v_max3_f32 v0, v0, v90, v91
	v_max3_f32 v0, v0, v92, v93
	v_max3_f32 v0, v0, v94, v95
	v_mov_b32_e32 v2, v0
	s_nop 1
	v_permlane32_swap_b32_e32 v0, v2
	v_max_f32_e32 v2, v2, v2
	v_max_f32_e32 v0, v0, v0
	v_max_f32_e32 v0, v0, v2
	v_cmp_ge_f32_e32 vcc, s28, v0
	s_cmp_eq_u64 vcc, exec
	s_cbranch_scc1 .LBB0_2906
	v_max_f32_e32 v0, v0, v0
	v_max_f32_e32 v2, 0, v0
	v_exp_f32_e64 v0, -v2
	v_add_f32_e32 v181, v181, v2
	v_sub_f32_e32 v111, v111, v2
	v_sub_f32_e32 v110, v110, v2
	v_pk_mul_f32 v[78:79], v[78:79], v[0:1] op_sel_hi:[1,0]
	v_pk_mul_f32 v[76:77], v[76:77], v[0:1] op_sel_hi:[1,0]
	v_pk_mul_f32 v[74:75], v[74:75], v[0:1] op_sel_hi:[1,0]
	v_pk_mul_f32 v[72:73], v[72:73], v[0:1] op_sel_hi:[1,0]
	v_pk_mul_f32 v[70:71], v[70:71], v[0:1] op_sel_hi:[1,0]
	v_pk_mul_f32 v[68:69], v[68:69], v[0:1] op_sel_hi:[1,0]
	v_pk_mul_f32 v[66:67], v[66:67], v[0:1] op_sel_hi:[1,0]
	v_pk_mul_f32 v[64:65], v[64:65], v[0:1] op_sel_hi:[1,0]
	v_pk_mul_f32 v[62:63], v[62:63], v[0:1] op_sel_hi:[1,0]
	v_pk_mul_f32 v[60:61], v[60:61], v[0:1] op_sel_hi:[1,0]
	v_pk_mul_f32 v[58:59], v[58:59], v[0:1] op_sel_hi:[1,0]
	v_pk_mul_f32 v[56:57], v[56:57], v[0:1] op_sel_hi:[1,0]
	v_pk_mul_f32 v[54:55], v[54:55], v[0:1] op_sel_hi:[1,0]
	v_pk_mul_f32 v[52:53], v[52:53], v[0:1] op_sel_hi:[1,0]
	v_pk_mul_f32 v[50:51], v[50:51], v[0:1] op_sel_hi:[1,0]
	v_pk_mul_f32 v[48:49], v[48:49], v[0:1] op_sel_hi:[1,0]
	v_pk_mul_f32 v[46:47], v[46:47], v[0:1] op_sel_hi:[1,0]
	v_pk_mul_f32 v[44:45], v[44:45], v[0:1] op_sel_hi:[1,0]
	v_pk_mul_f32 v[42:43], v[42:43], v[0:1] op_sel_hi:[1,0]
	v_pk_mul_f32 v[40:41], v[40:41], v[0:1] op_sel_hi:[1,0]
	v_pk_mul_f32 v[38:39], v[38:39], v[0:1] op_sel_hi:[1,0]
	v_pk_mul_f32 v[36:37], v[36:37], v[0:1] op_sel_hi:[1,0]
	v_pk_mul_f32 v[34:35], v[34:35], v[0:1] op_sel_hi:[1,0]
	v_pk_mul_f32 v[32:33], v[32:33], v[0:1] op_sel_hi:[1,0]
	v_pk_mul_f32 v[30:31], v[30:31], v[0:1] op_sel_hi:[1,0]
	v_pk_mul_f32 v[28:29], v[28:29], v[0:1] op_sel_hi:[1,0]
	v_pk_mul_f32 v[26:27], v[26:27], v[0:1] op_sel_hi:[1,0]
	v_pk_mul_f32 v[24:25], v[24:25], v[0:1] op_sel_hi:[1,0]
	v_pk_mul_f32 v[22:23], v[22:23], v[0:1] op_sel_hi:[1,0]
	v_pk_mul_f32 v[20:21], v[20:21], v[0:1] op_sel_hi:[1,0]
	v_pk_mul_f32 v[18:19], v[18:19], v[0:1] op_sel_hi:[1,0]
	v_pk_mul_f32 v[16:17], v[16:17], v[0:1] op_sel_hi:[1,0]
	v_sub_f32_e32 v109, v109, v2
	v_sub_f32_e32 v108, v108, v2
	v_sub_f32_e32 v107, v107, v2
	v_sub_f32_e32 v106, v106, v2
	v_sub_f32_e32 v105, v105, v2
	v_sub_f32_e32 v104, v104, v2
	v_sub_f32_e32 v103, v103, v2
	v_sub_f32_e32 v102, v102, v2
	v_sub_f32_e32 v101, v101, v2
	v_sub_f32_e32 v100, v100, v2
	v_sub_f32_e32 v99, v99, v2
	v_sub_f32_e32 v98, v98, v2
	v_sub_f32_e32 v97, v97, v2
	v_sub_f32_e32 v96, v96, v2
	v_sub_f32_e32 v95, v95, v2
	v_sub_f32_e32 v94, v94, v2
	v_sub_f32_e32 v93, v93, v2
	v_sub_f32_e32 v92, v92, v2
	v_sub_f32_e32 v91, v91, v2
	v_sub_f32_e32 v90, v90, v2
	v_sub_f32_e32 v89, v89, v2
	v_sub_f32_e32 v88, v88, v2
	v_sub_f32_e32 v87, v87, v2
	v_sub_f32_e32 v86, v86, v2
	v_sub_f32_e32 v85, v85, v2
	v_sub_f32_e32 v84, v84, v2
	v_sub_f32_e32 v83, v83, v2
	v_sub_f32_e32 v82, v82, v2
	v_sub_f32_e32 v81, v81, v2
	v_sub_f32_e32 v80, v80, v2
	v_mul_f32_e32 v171, v171, v0
